# WIN sigmoid-only units (pn 11..19): -log2(e) folded into the row scale once; 161 per-element multiplies removed (31 became moves)
# speedup vs baseline: 1.0019x; 1.0019x over previous
.LBB0_421:
	s_waitcnt vmcnt(0)
	v_add_f32_e32 v0, v162, v163
	v_add_f32_e32 v162, v164, v165
	v_add_f32_e32 v0, v0, v162
	v_fmamk_f32 v0, v0, 0x3a800000, v222
	v_rsq_f32_e32 v164, v0
	v_add_f32_e32 v0, v154, v155
	v_add_f32_e32 v154, v156, v157
	v_add_f32_e32 v0, v0, v154
	v_fmamk_f32 v0, v0, 0x3a800000, v222
	v_rsq_f32_e32 v162, v0
	v_add_f32_e32 v0, v142, v143
	v_add_f32_e32 v142, v144, v145
	v_add_f32_e32 v0, v0, v142
	v_fmamk_f32 v0, v0, 0x3a800000, v222
	v_rsq_f32_e32 v156, v0
	v_add_f32_e32 v0, v158, v159
	v_add_f32_e32 v142, v160, v161
	v_add_f32_e32 v0, v0, v142
	v_fmamk_f32 v0, v0, 0x3a800000, v222
	v_rsq_f32_e32 v154, v0
	v_add_f32_e32 v0, v150, v151
	v_add_f32_e32 v142, v152, v153
	v_add_f32_e32 v0, v0, v142
	v_fmamk_f32 v0, v0, 0x3a800000, v222
	v_rsq_f32_e32 v144, v0
	v_add_f32_e32 v0, v146, v147
	v_add_f32_e32 v142, v148, v149
	v_add_f32_e32 v0, v0, v142
	v_fmamk_f32 v0, v0, 0x3a800000, v222
	v_rsq_f32_e32 v142, v0
	v_add_f32_e32 v0, v138, v139
	v_add_f32_e32 v138, v140, v141
	v_add_f32_e32 v0, v0, v138
	v_fmamk_f32 v0, v0, 0x3a800000, v222
	v_rsq_f32_e32 v138, v0
	v_add_f32_e32 v0, v134, v135
	v_add_f32_e32 v134, v136, v137
	v_add_f32_e32 v0, v0, v134
	v_fmamk_f32 v0, v0, 0x3a800000, v222
	v_rsq_f32_e32 v134, v0
	s_cmp_lt_u32 s78, 11
	s_cbranch_scc1 .Lwin_noscale
	v_mul_f32_e32 v164, 0xbfb8aa3b, v164
	v_mul_f32_e32 v162, 0xbfb8aa3b, v162
	v_mul_f32_e32 v156, 0xbfb8aa3b, v156
	v_mul_f32_e32 v154, 0xbfb8aa3b, v154
	v_mul_f32_e32 v144, 0xbfb8aa3b, v144
	v_mul_f32_e32 v142, 0xbfb8aa3b, v142
	v_mul_f32_e32 v138, 0xbfb8aa3b, v138
	v_mul_f32_e32 v134, 0xbfb8aa3b, v134
.Lwin_noscale:
	s_mov_b64 s[78:79], -1
	s_add_i32 s66, s87, s81
	v_lshlrev_b32_e32 v135, 5, v184
	s_andn2_b64 vcc, exec, s[74:75]
	s_cbranch_vccz .LBB0_437
	s_xor_b64 s[76:77], s[76:77], -1
	s_mov_b64 s[74:75], -1
	s_and_b64 vcc, exec, s[76:77]
	s_cbranch_vccz .LBB0_434
	s_xor_b64 s[74:75], s[72:73], -1
	s_mov_b64 s[72:73], -1
	s_and_b64 vcc, exec, s[74:75]
	s_cbranch_vccz .LBB0_431
	s_xor_b64 s[72:73], s[70:71], -1
	s_mov_b64 s[70:71], -1
	s_and_b64 vcc, exec, s[72:73]
	s_cbranch_vccz .LBB0_428
	s_and_b64 s[68:69], s[54:55], s[68:69]
	s_andn2_b64 vcc, exec, s[68:69]
	s_cbranch_vccnz .LBB0_427
	v_pk_mul_f32 v[136:137], v[132:133], v[164:165] op_sel_hi:[1,0]
	v_pk_mul_f32 v[140:141], v[130:131], v[164:165] op_sel_hi:[1,0]
	v_exp_f32_e32 v139, v140
	v_exp_f32_e32 v136, v136
	s_ashr_i32 s67, s57, 11
	s_mul_hi_i32 s69, s67, 0x1414000
	v_add_f32_e32 v139, 1.0, v139
	v_add_f32_e32 v136, 1.0, v136
	v_rcp_f32_e32 v146, v139
	v_rcp_f32_e32 v148, v136
	v_exp_f32_e32 v139, v141
	v_exp_f32_e32 v136, v137
	s_mul_i32 s67, s67, 0x1414000
	v_and_b32_e32 v0, 0xf9e0, v135
	v_add_f32_e32 v139, 1.0, v139
	v_add_f32_e32 v136, 1.0, v136
	v_rcp_f32_e32 v147, v139
	v_rcp_f32_e32 v149, v136
	s_add_u32 s68, s52, s67
	s_addc_u32 s69, s53, s69
	v_lshlrev_b32_e32 v0, 2, v0
	v_lshl_add_u64 v[136:137], s[68:69], 0, v[0:1]
	v_lshlrev_b32_e32 v0, 2, v170
	v_lshl_add_u64 v[136:137], v[136:137], 0, v[0:1]
	flat_store_dwordx4 v[136:137], v[146:149]
	v_pk_mul_f32 v[140:141], v[128:129], v[164:165] op_sel_hi:[1,0]
	s_movk_i32 s70, 0x1000
	v_pk_mul_f32 v[146:147], v[126:127], v[164:165] op_sel_hi:[1,0]
	s_mov_b32 s67, 0x1414000
	v_exp_f32_e32 v139, v146
	s_nop 0
	v_add_f32_e32 v139, 1.0, v139
	v_rcp_f32_e32 v146, v139
	v_exp_f32_e32 v139, v147
	s_nop 0
	v_add_f32_e32 v139, 1.0, v139
	v_rcp_f32_e32 v147, v139
	v_exp_f32_e32 v139, v140
	s_nop 0
	v_add_f32_e32 v139, 1.0, v139
	v_rcp_f32_e32 v148, v139
	v_exp_f32_e32 v139, v141
	v_pk_mul_f32 v[140:141], v[124:125], v[162:163] op_sel_hi:[1,0]
	v_add_f32_e32 v139, 1.0, v139
	v_rcp_f32_e32 v149, v139
	flat_store_dwordx4 v[136:137], v[146:149] offset:64
	s_nop 1
	v_pk_mul_f32 v[146:147], v[122:123], v[162:163] op_sel_hi:[1,0]
	s_nop 0
	v_exp_f32_e32 v139, v146
	s_nop 0
	v_add_f32_e32 v139, 1.0, v139
	v_rcp_f32_e32 v146, v139
	v_exp_f32_e32 v139, v147
	s_nop 0
	v_add_f32_e32 v139, 1.0, v139
	v_rcp_f32_e32 v147, v139
	v_exp_f32_e32 v139, v140
	s_nop 0
	v_add_f32_e32 v139, 1.0, v139
	v_rcp_f32_e32 v148, v139
	v_exp_f32_e32 v139, v141
	v_pk_mul_f32 v[140:141], v[120:121], v[162:163] op_sel_hi:[1,0]
	v_add_f32_e32 v139, 1.0, v139
	v_rcp_f32_e32 v149, v139
	flat_store_dwordx4 v[136:137], v[146:149] offset:2048
	s_nop 1
	v_pk_mul_f32 v[146:147], v[118:119], v[162:163] op_sel_hi:[1,0]
	s_nop 0
	v_exp_f32_e32 v139, v146
	s_nop 0
	v_add_f32_e32 v139, 1.0, v139
	v_rcp_f32_e32 v146, v139
	v_exp_f32_e32 v139, v147
	s_nop 0
	v_add_f32_e32 v139, 1.0, v139
	v_rcp_f32_e32 v147, v139
	v_exp_f32_e32 v139, v140
	s_nop 0
	v_add_f32_e32 v139, 1.0, v139
	v_rcp_f32_e32 v148, v139
	v_exp_f32_e32 v139, v141
	v_pk_mul_f32 v[140:141], v[116:117], v[156:157] op_sel_hi:[1,0]
	v_add_f32_e32 v139, 1.0, v139
	v_rcp_f32_e32 v149, v139
	flat_store_dwordx4 v[136:137], v[146:149] offset:2112
	s_nop 1
	v_pk_mul_f32 v[146:147], v[114:115], v[156:157] op_sel_hi:[1,0]
	v_add_co_u32_e32 v136, vcc, s70, v136
	v_exp_f32_e32 v139, v146
	v_addc_co_u32_e32 v137, vcc, 0, v137, vcc
	v_add_f32_e32 v139, 1.0, v139
	v_rcp_f32_e32 v146, v139
	v_exp_f32_e32 v139, v147
	s_nop 0
	v_add_f32_e32 v139, 1.0, v139
	v_rcp_f32_e32 v147, v139
	v_exp_f32_e32 v139, v140
	s_nop 0
	v_add_f32_e32 v139, 1.0, v139
	v_rcp_f32_e32 v148, v139
	v_exp_f32_e32 v139, v141
	v_pk_mul_f32 v[140:141], v[112:113], v[156:157] op_sel_hi:[1,0]
	v_add_f32_e32 v139, 1.0, v139
	v_rcp_f32_e32 v149, v139
	flat_store_dwordx4 v[136:137], v[146:149]
	s_nop 1
	v_pk_mul_f32 v[146:147], v[110:111], v[156:157] op_sel_hi:[1,0]
	s_nop 0
	v_exp_f32_e32 v139, v146
	s_nop 0
	v_add_f32_e32 v139, 1.0, v139
	v_rcp_f32_e32 v146, v139
	v_exp_f32_e32 v139, v147
	s_nop 0
	v_add_f32_e32 v139, 1.0, v139
	v_rcp_f32_e32 v147, v139
	v_exp_f32_e32 v139, v140
	s_nop 0
	v_add_f32_e32 v139, 1.0, v139
	v_rcp_f32_e32 v148, v139
	v_exp_f32_e32 v139, v141
	v_pk_mul_f32 v[140:141], v[108:109], v[154:155] op_sel_hi:[1,0]
	v_add_f32_e32 v139, 1.0, v139
	v_rcp_f32_e32 v149, v139
	flat_store_dwordx4 v[136:137], v[146:149] offset:64
	s_nop 1
	v_pk_mul_f32 v[146:147], v[106:107], v[154:155] op_sel_hi:[1,0]
	s_nop 0
	v_exp_f32_e32 v139, v146
	s_nop 0
	v_add_f32_e32 v139, 1.0, v139
	v_rcp_f32_e32 v146, v139
	v_exp_f32_e32 v139, v147
	s_nop 0
	v_add_f32_e32 v139, 1.0, v139
	v_rcp_f32_e32 v147, v139
	v_exp_f32_e32 v139, v140
	s_nop 0
	v_add_f32_e32 v139, 1.0, v139
	v_rcp_f32_e32 v148, v139
	v_exp_f32_e32 v139, v141
	v_pk_mul_f32 v[140:141], v[104:105], v[154:155] op_sel_hi:[1,0]
	v_add_f32_e32 v139, 1.0, v139
	v_rcp_f32_e32 v149, v139
	flat_store_dwordx4 v[136:137], v[146:149] offset:2048
	s_nop 1
	v_pk_mul_f32 v[146:147], v[102:103], v[154:155] op_sel_hi:[1,0]
	s_nop 0
	v_exp_f32_e32 v139, v146
	s_nop 0
	v_add_f32_e32 v139, 1.0, v139
	v_rcp_f32_e32 v146, v139
	v_exp_f32_e32 v139, v147
	s_nop 0
	v_add_f32_e32 v139, 1.0, v139
	v_rcp_f32_e32 v147, v139
	v_exp_f32_e32 v139, v140
	s_nop 0
	v_add_f32_e32 v139, 1.0, v139
	v_rcp_f32_e32 v148, v139
	v_exp_f32_e32 v139, v141
	v_pk_mul_f32 v[140:141], v[98:99], v[144:145] op_sel_hi:[1,0]
	v_add_f32_e32 v139, 1.0, v139
	v_rcp_f32_e32 v149, v139
	v_exp_f32_e32 v140, v140
	v_ashrrev_i32_e32 v139, 11, v182
	flat_store_dwordx4 v[136:137], v[146:149] offset:2112
	v_pk_mul_f32 v[136:137], v[100:101], v[144:145] op_sel_hi:[1,0]
	v_add_f32_e32 v140, 1.0, v140
	v_exp_f32_e32 v136, v136
	v_rcp_f32_e32 v146, v140
	v_exp_f32_e32 v140, v141
	v_add_f32_e32 v136, 1.0, v136
	v_rcp_f32_e32 v148, v136
	v_exp_f32_e32 v136, v137
	v_add_f32_e32 v140, 1.0, v140
	v_rcp_f32_e32 v147, v140
	v_mov_b32_e32 v141, v1
	v_add_f32_e32 v136, 1.0, v136
	v_rcp_f32_e32 v149, v136
	v_mov_b64_e32 v[136:137], s[52:53]
	v_mad_i64_i32 v[136:137], s[68:69], v139, s67, v[136:137]
	v_lshlrev_b32_e32 v139, 7, v182
	v_and_b32_e32 v140, 0x3e780, v139
	v_lshl_add_u64 v[136:137], v[136:137], 0, v[140:141]
	v_lshl_add_u64 v[136:137], v[136:137], 0, v[0:1]
	flat_store_dwordx4 v[136:137], v[146:149]
	v_pk_mul_f32 v[140:141], v[92:93], v[144:145] op_sel_hi:[1,0]
	s_nop 0
	v_pk_mul_f32 v[146:147], v[90:91], v[144:145] op_sel_hi:[1,0]
	s_nop 0
	v_exp_f32_e32 v0, v146
	s_nop 0
	v_add_f32_e32 v0, 1.0, v0
	v_rcp_f32_e32 v146, v0
	v_exp_f32_e32 v0, v147
	s_nop 0
	v_add_f32_e32 v0, 1.0, v0
	v_rcp_f32_e32 v147, v0
	v_exp_f32_e32 v0, v140
	s_nop 0
	v_add_f32_e32 v0, 1.0, v0
	v_rcp_f32_e32 v148, v0
	v_exp_f32_e32 v0, v141
	v_pk_mul_f32 v[140:141], v[88:89], v[142:143] op_sel_hi:[1,0]
	v_add_f32_e32 v0, 1.0, v0
	v_rcp_f32_e32 v149, v0
	flat_store_dwordx4 v[136:137], v[146:149] offset:64
	s_nop 1
	v_pk_mul_f32 v[146:147], v[86:87], v[142:143] op_sel_hi:[1,0]
	s_nop 0
	v_exp_f32_e32 v0, v146
	s_nop 0
	v_add_f32_e32 v0, 1.0, v0
	v_rcp_f32_e32 v146, v0
	v_exp_f32_e32 v0, v147
	s_nop 0
	v_add_f32_e32 v0, 1.0, v0
	v_rcp_f32_e32 v147, v0
	v_exp_f32_e32 v0, v140
	s_nop 0
	v_add_f32_e32 v0, 1.0, v0
	v_rcp_f32_e32 v148, v0
	v_exp_f32_e32 v0, v141
	v_pk_mul_f32 v[140:141], v[84:85], v[142:143] op_sel_hi:[1,0]
	v_add_f32_e32 v0, 1.0, v0
	v_rcp_f32_e32 v149, v0
	flat_store_dwordx4 v[136:137], v[146:149] offset:2048
	s_nop 1
	v_pk_mul_f32 v[146:147], v[82:83], v[142:143] op_sel_hi:[1,0]
	s_nop 0
	v_exp_f32_e32 v0, v146
	s_nop 0
	v_add_f32_e32 v0, 1.0, v0
	v_rcp_f32_e32 v146, v0
	v_exp_f32_e32 v0, v147
	s_nop 0
	v_add_f32_e32 v0, 1.0, v0
	v_rcp_f32_e32 v147, v0
	v_exp_f32_e32 v0, v140
	s_nop 0
	v_add_f32_e32 v0, 1.0, v0
	v_rcp_f32_e32 v148, v0
	v_exp_f32_e32 v0, v141
	v_pk_mul_f32 v[140:141], v[80:81], v[138:139] op_sel_hi:[1,0]
	v_add_f32_e32 v0, 1.0, v0
	v_rcp_f32_e32 v149, v0
	flat_store_dwordx4 v[136:137], v[146:149] offset:2112
	s_nop 1
	v_pk_mul_f32 v[146:147], v[78:79], v[138:139] op_sel_hi:[1,0]
	v_add_co_u32_e32 v136, vcc, s70, v136
	v_exp_f32_e32 v0, v146
	v_addc_co_u32_e32 v137, vcc, 0, v137, vcc
	v_add_f32_e32 v0, 1.0, v0
	v_rcp_f32_e32 v146, v0
	v_exp_f32_e32 v0, v147
	s_nop 0
	v_add_f32_e32 v0, 1.0, v0
	v_rcp_f32_e32 v147, v0
	v_exp_f32_e32 v0, v140
	s_nop 0
	v_add_f32_e32 v0, 1.0, v0
	v_rcp_f32_e32 v148, v0
	v_exp_f32_e32 v0, v141
	v_pk_mul_f32 v[140:141], v[76:77], v[138:139] op_sel_hi:[1,0]
	v_add_f32_e32 v0, 1.0, v0
	v_rcp_f32_e32 v149, v0
	flat_store_dwordx4 v[136:137], v[146:149]
	s_nop 1
	v_pk_mul_f32 v[146:147], v[74:75], v[138:139] op_sel_hi:[1,0]
	s_nop 0
	v_exp_f32_e32 v0, v146
	s_nop 0
	v_add_f32_e32 v0, 1.0, v0
	v_rcp_f32_e32 v146, v0
	v_exp_f32_e32 v0, v147
	s_nop 0
	v_add_f32_e32 v0, 1.0, v0
	v_rcp_f32_e32 v147, v0
	v_exp_f32_e32 v0, v140
	s_nop 0
	v_add_f32_e32 v0, 1.0, v0
	v_rcp_f32_e32 v148, v0
	v_exp_f32_e32 v0, v141
	v_pk_mul_f32 v[140:141], v[72:73], v[134:135] op_sel_hi:[1,0]
	v_add_f32_e32 v0, 1.0, v0
	v_rcp_f32_e32 v149, v0
	flat_store_dwordx4 v[136:137], v[146:149] offset:64
	s_nop 1
	v_pk_mul_f32 v[146:147], v[70:71], v[134:135] op_sel_hi:[1,0]
	s_nop 0
	v_exp_f32_e32 v0, v146
	s_nop 0
	v_add_f32_e32 v0, 1.0, v0
	v_rcp_f32_e32 v146, v0
	v_exp_f32_e32 v0, v147
	s_nop 0
	v_add_f32_e32 v0, 1.0, v0
	v_rcp_f32_e32 v147, v0
	v_exp_f32_e32 v0, v140
	s_nop 0
	v_add_f32_e32 v0, 1.0, v0
	v_rcp_f32_e32 v148, v0
	v_exp_f32_e32 v0, v141
	v_pk_mul_f32 v[140:141], v[68:69], v[134:135] op_sel_hi:[1,0]
	v_add_f32_e32 v0, 1.0, v0
	v_rcp_f32_e32 v149, v0
	flat_store_dwordx4 v[136:137], v[146:149] offset:2048
	s_nop 1
	v_pk_mul_f32 v[146:147], v[66:67], v[134:135] op_sel_hi:[1,0]
	s_nop 0
	v_exp_f32_e32 v0, v146
	s_nop 0
	v_add_f32_e32 v0, 1.0, v0
	v_rcp_f32_e32 v146, v0
	v_exp_f32_e32 v0, v147
	s_nop 0
	v_add_f32_e32 v0, 1.0, v0
	v_rcp_f32_e32 v147, v0
	v_exp_f32_e32 v0, v140
	s_nop 0
	v_add_f32_e32 v0, 1.0, v0
	v_rcp_f32_e32 v148, v0
	v_exp_f32_e32 v0, v141
	s_nop 0
	v_add_f32_e32 v0, 1.0, v0
	v_rcp_f32_e32 v149, v0
	flat_store_dwordx4 v[136:137], v[146:149] offset:2112

.LBB0_428:
	s_andn2_b64 vcc, exec, s[70:71]
	s_cbranch_vccnz .LBB0_430
	s_lshl_b64 s[68:69], s[6:7], 1
	s_add_u32 s6, s64, s68
	s_addc_u32 s67, s65, s69
	s_lshl_b32 s68, s29, 1
	s_add_u32 s68, s6, s68
	s_addc_u32 s69, s67, 0
	v_lshlrev_b32_e32 v0, 1, v168
	v_pk_mul_f32 v[148:149], v[130:131], v[164:165] op_sel_hi:[1,0]
	v_lshl_add_u64 v[136:137], s[68:69], 0, v[0:1]
	v_pk_mul_f32 v[146:147], v[132:133], v[164:165] op_sel_hi:[1,0]
	v_mov_b32_e32 v0, v148
	v_mov_b32_e32 v139, v149
	v_pk_mul_f32 v[148:149], v[126:127], v[164:165] op_sel_hi:[1,0]
	v_mov_b32_e32 v143, v146
	v_mov_b32_e32 v145, v147
	v_exp_f32_e32 v146, v148
	v_exp_f32_e32 v147, v149
	v_pk_mul_f32 v[150:151], v[128:129], v[164:165] op_sel_hi:[1,0]
	v_add_f32_e32 v146, 1.0, v146
	v_exp_f32_e32 v0, v0
	v_exp_f32_e32 v139, v139
	v_rcp_f32_e32 v148, v146
	v_add_f32_e32 v146, 1.0, v147
	v_exp_f32_e32 v147, v150
	v_exp_f32_e32 v143, v143
	v_exp_f32_e32 v145, v145
	v_exp_f32_e32 v149, v151
	v_add_f32_e32 v0, 1.0, v0
	v_add_f32_e32 v139, 1.0, v139
	v_rcp_f32_e32 v0, v0
	v_rcp_f32_e32 v139, v139
	v_rcp_f32_e32 v150, v146
	v_add_f32_e32 v146, 1.0, v147
	v_add_f32_e32 v143, 1.0, v143
	v_add_f32_e32 v145, 1.0, v145
	v_rcp_f32_e32 v151, v146
	v_add_f32_e32 v146, 1.0, v149
	v_rcp_f32_e32 v143, v143
	v_rcp_f32_e32 v145, v145
	v_rcp_f32_e32 v149, v146
	s_ashr_i32 s6, s57, 11
	v_cvt_pk_bf16_f32 v146, v0, v139
	v_lshlrev_b32_e32 v0, 11, v184
	v_mad_i64_i32 v[140:141], s[68:69], s6, v224, v[136:137]
	v_and_b32_e32 v0, 0x3e7800, v0
	v_cvt_pk_bf16_f32 v147, v143, v145
	v_cvt_pk_bf16_f32 v148, v148, v150
	v_cvt_pk_bf16_f32 v149, v151, v149
	v_lshl_add_u64 v[140:141], v[140:141], 0, v[0:1]
	flat_store_dwordx4 v[140:141], v[146:149]
	v_pk_mul_f32 v[150:151], v[120:121], v[162:163] op_sel_hi:[1,0]
	s_mov_b32 s70, 0x8000
	v_pk_mul_f32 v[148:149], v[122:123], v[162:163] op_sel_hi:[1,0]
	v_pk_mul_f32 v[146:147], v[124:125], v[162:163] op_sel_hi:[1,0]
	v_mov_b32_e32 v0, v148
	v_mov_b32_e32 v139, v149
	v_pk_mul_f32 v[148:149], v[118:119], v[162:163] op_sel_hi:[1,0]
	v_mov_b32_e32 v143, v146
	v_mov_b32_e32 v145, v147
	v_exp_f32_e32 v146, v148
	v_exp_f32_e32 v147, v149
	v_add_f32_e32 v146, 1.0, v146
	v_rcp_f32_e32 v148, v146
	v_add_f32_e32 v146, 1.0, v147
	v_exp_f32_e32 v147, v150
	v_exp_f32_e32 v0, v0
	v_exp_f32_e32 v139, v139
	v_exp_f32_e32 v143, v143
	v_exp_f32_e32 v145, v145
	v_exp_f32_e32 v149, v151
	v_rcp_f32_e32 v150, v146
	v_add_f32_e32 v146, 1.0, v147
	v_add_f32_e32 v0, 1.0, v0
	v_add_f32_e32 v139, 1.0, v139
	v_add_f32_e32 v143, 1.0, v143
	v_add_f32_e32 v145, 1.0, v145
	v_rcp_f32_e32 v151, v146
	v_add_f32_e32 v146, 1.0, v149
	v_rcp_f32_e32 v0, v0
	v_rcp_f32_e32 v139, v139
	v_rcp_f32_e32 v143, v143
	v_rcp_f32_e32 v145, v145
	v_rcp_f32_e32 v149, v146
	v_cvt_pk_bf16_f32 v148, v148, v150
	v_add_co_u32_e32 v150, vcc, s70, v140
	v_cvt_pk_bf16_f32 v146, v0, v139
	v_cvt_pk_bf16_f32 v147, v143, v145
	v_cvt_pk_bf16_f32 v149, v151, v149
	v_addc_co_u32_e32 v151, vcc, 0, v141, vcc
	flat_store_dwordx4 v[150:151], v[146:149]
	v_pk_mul_f32 v[150:151], v[112:113], v[156:157] op_sel_hi:[1,0]
	s_mov_b32 s6, 0x10000
	v_pk_mul_f32 v[148:149], v[114:115], v[156:157] op_sel_hi:[1,0]
	v_pk_mul_f32 v[146:147], v[116:117], v[156:157] op_sel_hi:[1,0]
	v_mov_b32_e32 v0, v148
	v_mov_b32_e32 v139, v149
	v_pk_mul_f32 v[148:149], v[110:111], v[156:157] op_sel_hi:[1,0]
	v_mov_b32_e32 v143, v146
	v_mov_b32_e32 v145, v147
	v_exp_f32_e32 v146, v148
	v_exp_f32_e32 v147, v149
	v_add_f32_e32 v146, 1.0, v146
	v_rcp_f32_e32 v148, v146
	v_add_f32_e32 v146, 1.0, v147
	v_exp_f32_e32 v147, v150
	v_exp_f32_e32 v0, v0
	v_exp_f32_e32 v139, v139
	v_exp_f32_e32 v143, v143
	v_exp_f32_e32 v145, v145
	v_exp_f32_e32 v149, v151
	v_rcp_f32_e32 v150, v146
	v_add_f32_e32 v146, 1.0, v147
	v_add_f32_e32 v0, 1.0, v0
	v_add_f32_e32 v139, 1.0, v139
	v_add_f32_e32 v143, 1.0, v143
	v_add_f32_e32 v145, 1.0, v145
	v_rcp_f32_e32 v151, v146
	v_add_f32_e32 v146, 1.0, v149
	v_rcp_f32_e32 v0, v0
	v_rcp_f32_e32 v139, v139
	v_rcp_f32_e32 v143, v143
	v_rcp_f32_e32 v145, v145
	v_rcp_f32_e32 v149, v146
	v_cvt_pk_bf16_f32 v148, v148, v150
	v_add_co_u32_e32 v150, vcc, s6, v140
	v_cvt_pk_bf16_f32 v146, v0, v139
	v_cvt_pk_bf16_f32 v147, v143, v145
	v_cvt_pk_bf16_f32 v149, v151, v149
	v_addc_co_u32_e32 v151, vcc, 0, v141, vcc
	flat_store_dwordx4 v[150:151], v[146:149]
	v_pk_mul_f32 v[150:151], v[104:105], v[154:155] op_sel_hi:[1,0]
	s_mov_b32 s67, 0x18000
	v_pk_mul_f32 v[148:149], v[106:107], v[154:155] op_sel_hi:[1,0]
	v_pk_mul_f32 v[146:147], v[108:109], v[154:155] op_sel_hi:[1,0]
	v_mov_b32_e32 v0, v148
	v_mov_b32_e32 v139, v149
	v_pk_mul_f32 v[148:149], v[102:103], v[154:155] op_sel_hi:[1,0]
	v_mov_b32_e32 v143, v146
	v_mov_b32_e32 v145, v147
	v_exp_f32_e32 v146, v148
	v_exp_f32_e32 v147, v149
	v_add_f32_e32 v146, 1.0, v146
	v_rcp_f32_e32 v148, v146
	v_add_f32_e32 v146, 1.0, v147
	v_exp_f32_e32 v147, v150
	v_exp_f32_e32 v0, v0
	v_exp_f32_e32 v139, v139
	v_exp_f32_e32 v143, v143
	v_exp_f32_e32 v145, v145
	v_exp_f32_e32 v149, v151
	v_rcp_f32_e32 v150, v146
	v_add_f32_e32 v146, 1.0, v147
	v_add_f32_e32 v0, 1.0, v0
	v_add_f32_e32 v139, 1.0, v139
	v_add_f32_e32 v143, 1.0, v143
	v_add_f32_e32 v145, 1.0, v145
	v_rcp_f32_e32 v151, v146
	v_add_f32_e32 v146, 1.0, v149
	v_rcp_f32_e32 v0, v0
	v_rcp_f32_e32 v139, v139
	v_rcp_f32_e32 v143, v143
	v_rcp_f32_e32 v145, v145
	v_rcp_f32_e32 v149, v146
	v_add_co_u32_e32 v140, vcc, s67, v140
	v_cvt_pk_bf16_f32 v146, v0, v139
	v_cvt_pk_bf16_f32 v147, v143, v145
	v_cvt_pk_bf16_f32 v148, v148, v150
	v_cvt_pk_bf16_f32 v149, v151, v149
	v_addc_co_u32_e32 v141, vcc, 0, v141, vcc
	flat_store_dwordx4 v[140:141], v[146:149]
	v_ashrrev_i32_e32 v0, 11, v182
	s_mov_b32 s67, 0x1414000
	v_pk_mul_f32 v[146:147], v[98:99], v[144:145] op_sel_hi:[1,0]
	v_mad_i64_i32 v[136:137], s[68:69], v0, s67, v[136:137]
	v_pk_mul_f32 v[148:149], v[92:93], v[144:145] op_sel_hi:[1,0]
	v_mov_b32_e32 v0, v146
	v_mov_b32_e32 v139, v147
	v_pk_mul_f32 v[146:147], v[90:91], v[144:145] op_sel_hi:[1,0]
	v_pk_mul_f32 v[140:141], v[100:101], v[144:145] op_sel_hi:[1,0]
	v_exp_f32_e32 v0, v0
	v_exp_f32_e32 v139, v139
	v_mov_b32_e32 v143, v146
	v_mov_b32_e32 v145, v147
	v_exp_f32_e32 v146, v148
	v_exp_f32_e32 v140, v140
	v_exp_f32_e32 v141, v141
	v_exp_f32_e32 v143, v143
	v_exp_f32_e32 v145, v145
	v_exp_f32_e32 v147, v149
	v_add_f32_e32 v0, 1.0, v0
	v_add_f32_e32 v139, 1.0, v139
	v_rcp_f32_e32 v0, v0
	v_rcp_f32_e32 v139, v139
	v_add_f32_e32 v146, 1.0, v146
	v_add_f32_e32 v140, 1.0, v140
	v_add_f32_e32 v141, 1.0, v141
	v_add_f32_e32 v143, 1.0, v143
	v_add_f32_e32 v145, 1.0, v145
	v_rcp_f32_e32 v149, v146
	v_add_f32_e32 v146, 1.0, v147
	v_rcp_f32_e32 v140, v140
	v_rcp_f32_e32 v141, v141
	v_rcp_f32_e32 v143, v143
	v_rcp_f32_e32 v145, v145
	v_rcp_f32_e32 v150, v146
	v_cvt_pk_bf16_f32 v146, v0, v139
	v_lshlrev_b32_e32 v0, 11, v182
	v_and_b32_e32 v0, 0x3e7800, v0
	v_cvt_pk_bf16_f32 v147, v140, v141
	v_cvt_pk_bf16_f32 v148, v143, v145
	v_cvt_pk_bf16_f32 v149, v149, v150
	v_lshl_add_u64 v[136:137], v[136:137], 0, v[0:1]
	flat_store_dwordx4 v[136:137], v[146:149]
	v_pk_mul_f32 v[140:141], v[88:89], v[142:143] op_sel_hi:[1,0]
	s_nop 0
	v_pk_mul_f32 v[146:147], v[86:87], v[142:143] op_sel_hi:[1,0]
	v_pk_mul_f32 v[148:149], v[84:85], v[142:143] op_sel_hi:[1,0]
	v_mov_b32_e32 v0, v146
	v_mov_b32_e32 v139, v147
	v_pk_mul_f32 v[146:147], v[82:83], v[142:143] op_sel_hi:[1,0]
	v_mov_b32_e32 v143, v146
	v_exp_f32_e32 v140, v140
	v_exp_f32_e32 v141, v141
	v_mov_b32_e32 v145, v147
	v_exp_f32_e32 v146, v148
	v_exp_f32_e32 v0, v0
	v_exp_f32_e32 v139, v139
	v_exp_f32_e32 v143, v143
	v_exp_f32_e32 v145, v145
	v_exp_f32_e32 v147, v149
	v_add_f32_e32 v140, 1.0, v140
	v_add_f32_e32 v141, 1.0, v141
	v_add_f32_e32 v146, 1.0, v146
	v_add_f32_e32 v0, 1.0, v0
	v_add_f32_e32 v139, 1.0, v139
	v_rcp_f32_e32 v140, v140
	v_rcp_f32_e32 v141, v141
	v_add_f32_e32 v143, 1.0, v143
	v_add_f32_e32 v145, 1.0, v145
	v_rcp_f32_e32 v149, v146
	v_add_f32_e32 v146, 1.0, v147
	v_rcp_f32_e32 v0, v0
	v_rcp_f32_e32 v139, v139
	v_rcp_f32_e32 v143, v143
	v_rcp_f32_e32 v145, v145
	v_rcp_f32_e32 v150, v146
	v_cvt_pk_bf16_f32 v147, v140, v141
	v_add_co_u32_e32 v140, vcc, s70, v136
	v_cvt_pk_bf16_f32 v146, v0, v139
	v_cvt_pk_bf16_f32 v148, v143, v145
	v_cvt_pk_bf16_f32 v149, v149, v150
	v_addc_co_u32_e32 v141, vcc, 0, v137, vcc
	flat_store_dwordx4 v[140:141], v[146:149]
	v_pk_mul_f32 v[140:141], v[80:81], v[138:139] op_sel_hi:[1,0]
	s_nop 0
	v_pk_mul_f32 v[146:147], v[78:79], v[138:139] op_sel_hi:[1,0]
	v_pk_mul_f32 v[148:149], v[76:77], v[138:139] op_sel_hi:[1,0]
	v_exp_f32_e32 v139, v147
	v_mov_b32_e32 v0, v146
	v_pk_mul_f32 v[146:147], v[74:75], v[138:139] op_sel_hi:[1,0]
	v_exp_f32_e32 v140, v140
	v_mov_b32_e32 v143, v146
	v_exp_f32_e32 v141, v141
	v_mov_b32_e32 v145, v147
	v_exp_f32_e32 v146, v148
	v_exp_f32_e32 v0, v0
	v_exp_f32_e32 v143, v143
	v_exp_f32_e32 v145, v145
	v_exp_f32_e32 v147, v149
	v_add_f32_e32 v140, 1.0, v140
	v_add_f32_e32 v141, 1.0, v141
	v_add_f32_e32 v146, 1.0, v146
	v_add_f32_e32 v0, 1.0, v0
	v_add_f32_e32 v139, 1.0, v139
	v_rcp_f32_e32 v140, v140
	v_rcp_f32_e32 v141, v141
	v_add_f32_e32 v143, 1.0, v143
	v_add_f32_e32 v145, 1.0, v145
	v_rcp_f32_e32 v149, v146
	v_add_f32_e32 v146, 1.0, v147
	v_rcp_f32_e32 v0, v0
	v_rcp_f32_e32 v139, v139
	v_rcp_f32_e32 v143, v143
	v_rcp_f32_e32 v145, v145
	v_rcp_f32_e32 v150, v146
	v_cvt_pk_bf16_f32 v147, v140, v141
	v_add_co_u32_e32 v140, vcc, s6, v136
	v_cvt_pk_bf16_f32 v146, v0, v139
	v_cvt_pk_bf16_f32 v148, v143, v145
	v_cvt_pk_bf16_f32 v149, v149, v150
	v_addc_co_u32_e32 v141, vcc, 0, v137, vcc
	flat_store_dwordx4 v[140:141], v[146:149]
	v_pk_mul_f32 v[140:141], v[72:73], v[134:135] op_sel_hi:[1,0]
	v_add_co_u32_e32 v136, vcc, 0x18000, v136
	v_pk_mul_f32 v[146:147], v[70:71], v[134:135] op_sel_hi:[1,0]
	v_pk_mul_f32 v[148:149], v[68:69], v[134:135] op_sel_hi:[1,0]
	v_mov_b32_e32 v0, v146
	v_mov_b32_e32 v139, v147
	v_pk_mul_f32 v[146:147], v[66:67], v[134:135] op_sel_hi:[1,0]
	v_mov_b32_e32 v143, v146
	v_mov_b32_e32 v145, v147
	v_exp_f32_e32 v146, v148
	v_exp_f32_e32 v0, v0
	v_exp_f32_e32 v139, v139
	v_exp_f32_e32 v140, v140
	v_exp_f32_e32 v141, v141
	v_exp_f32_e32 v143, v143
	v_exp_f32_e32 v145, v145
	v_exp_f32_e32 v147, v149
	v_add_f32_e32 v146, 1.0, v146
	v_add_f32_e32 v0, 1.0, v0
	v_add_f32_e32 v139, 1.0, v139
	v_add_f32_e32 v140, 1.0, v140
	v_add_f32_e32 v141, 1.0, v141
	v_add_f32_e32 v143, 1.0, v143
	v_add_f32_e32 v145, 1.0, v145
	v_rcp_f32_e32 v149, v146
	v_add_f32_e32 v146, 1.0, v147
	v_rcp_f32_e32 v0, v0
	v_rcp_f32_e32 v139, v139
	v_rcp_f32_e32 v140, v140
	v_rcp_f32_e32 v141, v141
	v_rcp_f32_e32 v143, v143
	v_rcp_f32_e32 v145, v145
	v_rcp_f32_e32 v150, v146
	v_cvt_pk_bf16_f32 v146, v0, v139
	v_cvt_pk_bf16_f32 v147, v140, v141
	v_cvt_pk_bf16_f32 v148, v143, v145
	v_cvt_pk_bf16_f32 v149, v149, v150
	v_addc_co_u32_e32 v137, vcc, 0, v137, vcc
	flat_store_dwordx4 v[136:137], v[146:149]

.LBB0_471:
	s_xor_b64 s[68:69], s[68:69], -1
	s_andn2_b64 vcc, exec, s[68:69]
	s_mov_b64 s[68:69], -1
	s_cbranch_vccnz .LBB0_479
	s_xor_b64 s[68:69], s[72:73], -1
	s_andn2_b64 vcc, exec, s[68:69]
	s_mov_b64 s[68:69], -1
	s_cbranch_vccnz .LBB0_476
	s_andn2_b64 vcc, exec, s[70:71]
	s_cbranch_vccnz .LBB0_475
	v_pk_mul_f32 v[68:69], v[64:65], v[164:165] op_sel_hi:[1,0]
	v_pk_mul_f32 v[70:71], v[62:63], v[164:165] op_sel_hi:[1,0]
	v_exp_f32_e32 v68, v68
	v_exp_f32_e32 v69, v69
	v_exp_f32_e32 v76, v70
	v_exp_f32_e32 v77, v71
	v_pk_mul_f32 v[70:71], v[58:59], v[164:165] op_sel_hi:[1,0]
	v_add_f32_e32 v68, 1.0, v68
	v_rcp_f32_e32 v78, v68
	v_add_f32_e32 v68, 1.0, v69
	v_exp_f32_e32 v69, v70
	v_exp_f32_e32 v70, v71
	v_pk_mul_f32 v[74:75], v[60:61], v[164:165] op_sel_hi:[1,0]
	v_rcp_f32_e32 v71, v68
	v_add_f32_e32 v68, 1.0, v69
	v_rcp_f32_e32 v79, v68
	v_add_f32_e32 v68, 1.0, v70
	v_exp_f32_e32 v69, v74
	v_exp_f32_e32 v70, v75
	s_lshl_b64 s[68:69], s[6:7], 1
	v_rcp_f32_e32 v74, v68
	v_add_f32_e32 v68, 1.0, v69
	s_add_u32 s6, s64, s68
	v_rcp_f32_e32 v75, v68
	v_add_f32_e32 v68, 1.0, v70
	s_addc_u32 s59, s65, s69
	s_lshl_b32 s67, s29, 1
	v_add_f32_e32 v76, 1.0, v76
	v_add_f32_e32 v77, 1.0, v77
	v_rcp_f32_e32 v80, v68
	s_add_u32 s68, s6, s67
	v_rcp_f32_e32 v76, v76
	v_rcp_f32_e32 v77, v77
	s_addc_u32 s69, s59, 0
	v_lshlrev_b32_e32 v66, 1, v168
	v_mov_b32_e32 v67, v1
	v_lshl_add_u64 v[66:67], s[68:69], 0, v[66:67]
	s_ashr_i32 s6, s57, 11
	v_cvt_pk_bf16_f32 v70, v79, v74
	v_lshlrev_b32_e32 v74, 11, v184
	v_mad_i64_i32 v[72:73], s[68:69], s6, v224, v[66:67]
	v_cvt_pk_bf16_f32 v69, v78, v71
	v_cvt_pk_bf16_f32 v71, v75, v80
	v_and_b32_e32 v74, 0x3e7800, v74
	v_mov_b32_e32 v75, v1
	v_cvt_pk_bf16_f32 v68, v76, v77
	v_lshl_add_u64 v[72:73], v[72:73], 0, v[74:75]
	flat_store_dwordx4 v[72:73], v[68:71]
	v_pk_mul_f32 v[74:75], v[52:53], v[162:163] op_sel_hi:[1,0]
	s_mov_b32 s67, 0x8000
	v_pk_mul_f32 v[68:69], v[56:57], v[162:163] op_sel_hi:[1,0]
	v_pk_mul_f32 v[70:71], v[54:55], v[162:163] op_sel_hi:[1,0]
	v_exp_f32_e32 v68, v68
	v_exp_f32_e32 v69, v69
	v_exp_f32_e32 v76, v70
	v_exp_f32_e32 v77, v71
	v_pk_mul_f32 v[70:71], v[50:51], v[162:163] op_sel_hi:[1,0]
	v_add_f32_e32 v68, 1.0, v68
	v_rcp_f32_e32 v78, v68
	v_add_f32_e32 v68, 1.0, v69
	v_exp_f32_e32 v69, v70
	v_exp_f32_e32 v70, v71
	v_rcp_f32_e32 v71, v68
	v_add_f32_e32 v68, 1.0, v69
	v_rcp_f32_e32 v79, v68
	v_add_f32_e32 v68, 1.0, v70
	v_exp_f32_e32 v69, v74
	v_exp_f32_e32 v70, v75
	v_rcp_f32_e32 v74, v68
	v_add_f32_e32 v68, 1.0, v69
	v_add_f32_e32 v76, 1.0, v76
	v_add_f32_e32 v77, 1.0, v77
	v_rcp_f32_e32 v75, v68
	v_add_f32_e32 v68, 1.0, v70
	v_rcp_f32_e32 v76, v76
	v_rcp_f32_e32 v77, v77
	v_rcp_f32_e32 v80, v68
	v_cvt_pk_bf16_f32 v70, v79, v74
	v_add_co_u32_e32 v74, vcc, s67, v72
	v_cvt_pk_bf16_f32 v68, v76, v77
	v_cvt_pk_bf16_f32 v69, v78, v71
	v_cvt_pk_bf16_f32 v71, v75, v80
	v_addc_co_u32_e32 v75, vcc, 0, v73, vcc
	flat_store_dwordx4 v[74:75], v[68:71]
	v_pk_mul_f32 v[74:75], v[44:45], v[156:157] op_sel_hi:[1,0]
	s_mov_b32 s6, 0x10000
	v_pk_mul_f32 v[68:69], v[48:49], v[156:157] op_sel_hi:[1,0]
	v_pk_mul_f32 v[70:71], v[46:47], v[156:157] op_sel_hi:[1,0]
	v_exp_f32_e32 v68, v68
	v_exp_f32_e32 v69, v69
	v_exp_f32_e32 v76, v70
	v_exp_f32_e32 v77, v71
	v_pk_mul_f32 v[70:71], v[42:43], v[156:157] op_sel_hi:[1,0]
	v_add_f32_e32 v68, 1.0, v68
	v_rcp_f32_e32 v78, v68
	v_add_f32_e32 v68, 1.0, v69
	v_exp_f32_e32 v69, v70
	v_exp_f32_e32 v70, v71
	v_rcp_f32_e32 v71, v68
	v_add_f32_e32 v68, 1.0, v69
	v_rcp_f32_e32 v79, v68
	v_add_f32_e32 v68, 1.0, v70
	v_exp_f32_e32 v69, v74
	v_exp_f32_e32 v70, v75
	v_rcp_f32_e32 v74, v68
	v_add_f32_e32 v68, 1.0, v69
	v_add_f32_e32 v76, 1.0, v76
	v_add_f32_e32 v77, 1.0, v77
	v_rcp_f32_e32 v75, v68
	v_add_f32_e32 v68, 1.0, v70
	v_rcp_f32_e32 v76, v76
	v_rcp_f32_e32 v77, v77
	v_rcp_f32_e32 v80, v68
	v_cvt_pk_bf16_f32 v70, v79, v74
	v_add_co_u32_e32 v74, vcc, s6, v72
	v_cvt_pk_bf16_f32 v68, v76, v77
	v_cvt_pk_bf16_f32 v69, v78, v71
	v_cvt_pk_bf16_f32 v71, v75, v80
	v_addc_co_u32_e32 v75, vcc, 0, v73, vcc
	flat_store_dwordx4 v[74:75], v[68:71]
	v_pk_mul_f32 v[74:75], v[36:37], v[154:155] op_sel_hi:[1,0]
	s_mov_b32 s59, 0x18000
	v_pk_mul_f32 v[68:69], v[40:41], v[154:155] op_sel_hi:[1,0]
	v_pk_mul_f32 v[70:71], v[38:39], v[154:155] op_sel_hi:[1,0]
	v_exp_f32_e32 v68, v68
	v_exp_f32_e32 v69, v69
	v_exp_f32_e32 v76, v70
	v_exp_f32_e32 v77, v71
	v_pk_mul_f32 v[70:71], v[34:35], v[154:155] op_sel_hi:[1,0]
	v_add_f32_e32 v68, 1.0, v68
	v_rcp_f32_e32 v78, v68
	v_add_f32_e32 v68, 1.0, v69
	v_exp_f32_e32 v69, v70
	v_exp_f32_e32 v70, v71
	v_rcp_f32_e32 v71, v68
	v_add_f32_e32 v68, 1.0, v69
	v_rcp_f32_e32 v79, v68
	v_add_f32_e32 v68, 1.0, v70
	v_exp_f32_e32 v69, v74
	v_exp_f32_e32 v70, v75
	v_rcp_f32_e32 v74, v68
	v_add_f32_e32 v68, 1.0, v69
	v_add_f32_e32 v76, 1.0, v76
	v_add_f32_e32 v77, 1.0, v77
	v_rcp_f32_e32 v75, v68
	v_add_f32_e32 v68, 1.0, v70
	v_rcp_f32_e32 v76, v76
	v_rcp_f32_e32 v77, v77
	v_rcp_f32_e32 v80, v68
	v_add_co_u32_e32 v72, vcc, s59, v72
	v_cvt_pk_bf16_f32 v68, v76, v77
	v_cvt_pk_bf16_f32 v69, v78, v71
	v_cvt_pk_bf16_f32 v70, v79, v74
	v_cvt_pk_bf16_f32 v71, v75, v80
	v_addc_co_u32_e32 v73, vcc, 0, v73, vcc
	s_mov_b32 s59, 0x1414000
	flat_store_dwordx4 v[72:73], v[68:71]
	v_pk_mul_f32 v[72:73], v[28:29], v[144:145] op_sel_hi:[1,0]
	s_nop 0
	v_mad_i64_i32 v[70:71], s[68:69], v135, s59, v[66:67]
	v_pk_mul_f32 v[66:67], v[32:33], v[144:145] op_sel_hi:[1,0]
	v_pk_mul_f32 v[68:69], v[30:31], v[144:145] op_sel_hi:[1,0]
	v_exp_f32_e32 v66, v66
	v_exp_f32_e32 v67, v67
	v_exp_f32_e32 v74, v68
	v_exp_f32_e32 v75, v69
	v_pk_mul_f32 v[68:69], v[26:27], v[144:145] op_sel_hi:[1,0]
	v_add_f32_e32 v66, 1.0, v66
	v_rcp_f32_e32 v76, v66
	v_add_f32_e32 v66, 1.0, v67
	v_exp_f32_e32 v67, v68
	v_exp_f32_e32 v68, v69
	v_rcp_f32_e32 v69, v66
	v_add_f32_e32 v66, 1.0, v67
	v_rcp_f32_e32 v77, v66
	v_add_f32_e32 v66, 1.0, v68
	v_exp_f32_e32 v67, v72
	v_exp_f32_e32 v68, v73
	v_rcp_f32_e32 v72, v66
	v_add_f32_e32 v66, 1.0, v67
	v_rcp_f32_e32 v73, v66
	v_add_f32_e32 v66, 1.0, v68
	v_add_f32_e32 v74, 1.0, v74
	v_add_f32_e32 v75, 1.0, v75
	v_rcp_f32_e32 v78, v66
	v_rcp_f32_e32 v74, v74
	v_rcp_f32_e32 v75, v75
	v_cvt_pk_bf16_f32 v68, v77, v72
	v_lshlrev_b32_e32 v72, 11, v182
	v_cvt_pk_bf16_f32 v67, v76, v69
	v_cvt_pk_bf16_f32 v69, v73, v78
	v_and_b32_e32 v72, 0x3e7800, v72
	v_mov_b32_e32 v73, v1
	v_cvt_pk_bf16_f32 v66, v74, v75
	v_lshl_add_u64 v[70:71], v[70:71], 0, v[72:73]
	flat_store_dwordx4 v[70:71], v[66:69]
	v_pk_mul_f32 v[72:73], v[20:21], v[142:143] op_sel_hi:[1,0]
	s_nop 0
	v_pk_mul_f32 v[66:67], v[24:25], v[142:143] op_sel_hi:[1,0]
	v_pk_mul_f32 v[68:69], v[22:23], v[142:143] op_sel_hi:[1,0]
	v_exp_f32_e32 v66, v66
	v_exp_f32_e32 v67, v67
	v_exp_f32_e32 v74, v68
	v_exp_f32_e32 v75, v69
	v_pk_mul_f32 v[68:69], v[18:19], v[142:143] op_sel_hi:[1,0]
	v_add_f32_e32 v66, 1.0, v66
	v_rcp_f32_e32 v76, v66
	v_add_f32_e32 v66, 1.0, v67
	v_exp_f32_e32 v67, v68
	v_exp_f32_e32 v68, v69
	v_rcp_f32_e32 v69, v66
	v_add_f32_e32 v66, 1.0, v67
	v_rcp_f32_e32 v77, v66
	v_add_f32_e32 v66, 1.0, v68
	v_exp_f32_e32 v67, v72
	v_exp_f32_e32 v68, v73
	v_rcp_f32_e32 v72, v66
	v_add_f32_e32 v66, 1.0, v67
	v_add_f32_e32 v74, 1.0, v74
	v_add_f32_e32 v75, 1.0, v75
	v_rcp_f32_e32 v73, v66
	v_add_f32_e32 v66, 1.0, v68
	v_rcp_f32_e32 v74, v74
	v_rcp_f32_e32 v75, v75
	v_rcp_f32_e32 v78, v66
	v_cvt_pk_bf16_f32 v68, v77, v72
	v_add_co_u32_e32 v72, vcc, s67, v70
	v_cvt_pk_bf16_f32 v66, v74, v75
	v_cvt_pk_bf16_f32 v67, v76, v69
	v_cvt_pk_bf16_f32 v69, v73, v78
	v_addc_co_u32_e32 v73, vcc, 0, v71, vcc
	flat_store_dwordx4 v[72:73], v[66:69]
	v_pk_mul_f32 v[72:73], v[12:13], v[138:139] op_sel_hi:[1,0]
	s_nop 0
	v_pk_mul_f32 v[66:67], v[16:17], v[138:139] op_sel_hi:[1,0]
	v_pk_mul_f32 v[68:69], v[14:15], v[138:139] op_sel_hi:[1,0]
	v_exp_f32_e32 v66, v66
	v_exp_f32_e32 v67, v67
	v_exp_f32_e32 v74, v68
	v_exp_f32_e32 v75, v69
	v_pk_mul_f32 v[68:69], v[10:11], v[138:139] op_sel_hi:[1,0]
	v_add_f32_e32 v66, 1.0, v66
	v_rcp_f32_e32 v76, v66
	v_add_f32_e32 v66, 1.0, v67
	v_exp_f32_e32 v67, v68
	v_exp_f32_e32 v68, v69
	v_rcp_f32_e32 v69, v66
	v_add_f32_e32 v66, 1.0, v67
	v_rcp_f32_e32 v77, v66
	v_add_f32_e32 v66, 1.0, v68
	v_exp_f32_e32 v67, v72
	v_exp_f32_e32 v68, v73
	v_rcp_f32_e32 v72, v66
	v_add_f32_e32 v66, 1.0, v67
	v_add_f32_e32 v74, 1.0, v74
	v_add_f32_e32 v75, 1.0, v75
	v_rcp_f32_e32 v73, v66
	v_add_f32_e32 v66, 1.0, v68
	v_rcp_f32_e32 v74, v74
	v_rcp_f32_e32 v75, v75
	v_rcp_f32_e32 v78, v66
	v_cvt_pk_bf16_f32 v68, v77, v72
	v_add_co_u32_e32 v72, vcc, s6, v70
	v_cvt_pk_bf16_f32 v66, v74, v75
	v_cvt_pk_bf16_f32 v67, v76, v69
	v_cvt_pk_bf16_f32 v69, v73, v78
	v_addc_co_u32_e32 v73, vcc, 0, v71, vcc
	flat_store_dwordx4 v[72:73], v[66:69]
	v_pk_mul_f32 v[72:73], v[4:5], v[134:135] op_sel_hi:[1,0]
	v_add_co_u32_e32 v70, vcc, 0x18000, v70
	v_pk_mul_f32 v[66:67], v[8:9], v[134:135] op_sel_hi:[1,0]
	v_pk_mul_f32 v[68:69], v[6:7], v[134:135] op_sel_hi:[1,0]
	v_exp_f32_e32 v66, v66
	v_exp_f32_e32 v67, v67
	v_exp_f32_e32 v74, v68
	v_exp_f32_e32 v75, v69
	v_pk_mul_f32 v[68:69], v[2:3], v[134:135] op_sel_hi:[1,0]
	v_add_f32_e32 v66, 1.0, v66
	v_rcp_f32_e32 v76, v66
	v_add_f32_e32 v66, 1.0, v67
	v_exp_f32_e32 v67, v68
	v_exp_f32_e32 v68, v69
	v_rcp_f32_e32 v69, v66
	v_add_f32_e32 v66, 1.0, v67
	v_rcp_f32_e32 v77, v66
	v_add_f32_e32 v66, 1.0, v68
	v_exp_f32_e32 v67, v72
	v_exp_f32_e32 v68, v73
	v_rcp_f32_e32 v72, v66
	v_add_f32_e32 v66, 1.0, v67
	v_add_f32_e32 v74, 1.0, v74
	v_add_f32_e32 v75, 1.0, v75
	v_rcp_f32_e32 v73, v66
	v_add_f32_e32 v66, 1.0, v68
	v_rcp_f32_e32 v74, v74
	v_rcp_f32_e32 v75, v75
	v_rcp_f32_e32 v78, v66
	v_cvt_pk_bf16_f32 v67, v76, v69
	v_cvt_pk_bf16_f32 v68, v77, v72
	v_cvt_pk_bf16_f32 v66, v74, v75
	v_cvt_pk_bf16_f32 v69, v73, v78
	v_addc_co_u32_e32 v71, vcc, 0, v71, vcc
	flat_store_dwordx4 v[70:71], v[66:69]
